# K-tile LDS-DMA issued at the start of each attention half-step (slot already free) instead of after the QK segment
# speedup vs baseline: 1.0102x; 1.0102x over previous
; __device__ __forceinline__ void finishSM(f32x16& p0, f32x16& p1, float alpha, float& l_reg, bf16x8& pa0, bf16x8& pa1, bf16x8& pa2, bf16x8& pa3) {
;     for (int r = 0; r < 16; ++r) p1[r] = __builtin_amdgcn_exp2f(p1[r]);
;     float ps = 0; for (int r = 0; r < 16; ++r) ps += p0[r]; for (int r = 0; r < 16; ++r) ps += p1[r];
;     { auto rr = __builtin_amdgcn_permlane32_swap(__float_as_uint(ps), __float_as_uint(ps), false, false);
;       ps = __uint_as_float(rr[0]) + __uint_as_float(rr[1]); }
;     l_reg = l_reg * alpha + ps;
;     ...
;     PK4(p0, 0, pa0); PK4(p0, 8, pa1); PK4(p1, 0, pa2); PK4(p1, 8, pa3);
;     ...
; }
; template <int KB, bool SK>
; __device__ __forceinline__ void qkt(f32x16& p0, f32x16& p1, const char* K_lds, int r32, int hi, const bf16x8* qr, bool act) {
;     if (SK && !act) { const float NEG = -__builtin_inff();
; #pragma unroll
;         for (int r = 0; r < 16; ++r) { p0[r] = NEG; p1[r] = NEG; } return; }
;     p0 = f32x16{}; p1 = f32x16{};
;     const char* kb[4];
; #pragma unroll
;     for (int dd = 0; dd < 4; ++dd) kb[dd] = K_lds + KB * SHM_K + KSWZ(r32, (dd * 16 + hi * 8) * 2);
; #pragma unroll
;     for (int d0 = 0; d0 < 8; ++d0) { const char* a = kb[d0 & 3] + (d0 >> 2) * 128;
;         bf16x8 b0 = *reinterpret_cast<const bf16x8*>(a);
;         bf16x8 b1 = *reinterpret_cast<const bf16x8*>(a + 32 * 256);
;         const bf16x8 qf = qr[d0];
;         p0 = __builtin_amdgcn_mfma_f32_32x32x16_bf16(b0, qf, p0, 0, 0, 0);
;         p1 = __builtin_amdgcn_mfma_f32_32x32x16_bf16(b1, qf, p1, 0, 0, 0); }
; }
; template <int VB, bool SK>
; __device__ __forceinline__ void pv_tile(f32x16* o, int vb0, bf16x8 pa0, bf16x8 pa1, bf16x8 pa2, bf16x8 pa3, bool act) {
;     if (SK && !act) return;
;     ...
;     PV_D0(0); PV_D0(1); PV_D0(2); PV_D0(3);
;     ...
; }
.Lattn_prio_skip:
.LBB0_1129:
	v_readfirstlane_b32 s52, v1
	v_add_u32_e32 v248, 0x2000, v251
	s_nop 1
	s_lshl_b32 s52, s52, 4
	s_add_i32 m0, s52, 0x8000
	s_nop 0
	global_load_lds_dwordx4 v251, s[22:23]
	s_add_i32 m0, s52, 0xa000
	s_nop 0
	global_load_lds_dwordx4 v248, s[22:23]
	ds_read_b128 v[180:183], v211 offset:49152
	ds_read_b128 v[184:187], v211 offset:57344
	ds_read_b128 v[188:191], v212 offset:49152
	ds_read_b128 v[228:231], v212 offset:57344
	ds_read_b128 v[232:235], v213 offset:49152
	ds_read_b128 v[236:239], v213 offset:57344
	ds_read_b128 v[240:243], v214 offset:49152
	ds_read_b128 v[244:247], v214 offset:57344
	v_exp_f32_e32 v126, v126
	v_exp_f32_e32 v127, v127
	v_exp_f32_e32 v124, v124
	v_exp_f32_e32 v125, v125
	v_exp_f32_e32 v120, v120
	v_exp_f32_e32 v121, v121
	s_add_i32 s4, s26, 0xffffff81
	s_sub_i32 s5, s26, 64
	s_waitcnt lgkmcnt(7)
	v_mfma_f32_32x32x16_bf16 v[86:101], v[180:183], v[158:161], 0
	ds_read_b128 v[180:183], v211 offset:49280
	v_exp_f32_e32 v116, v116
	v_exp_f32_e32 v117, v117
	v_exp_f32_e32 v114, v114
	v_exp_f32_e32 v115, v115
	v_exp_f32_e32 v128, v128
	s_waitcnt lgkmcnt(7)
	v_mfma_f32_32x32x16_bf16 v[70:85], v[184:187], v[158:161], 0
	ds_read_b128 v[184:187], v211 offset:57472
	v_exp_f32_e32 v129, v129
	v_exp_f32_e32 v122, v122
	v_exp_f32_e32 v123, v123
	v_exp_f32_e32 v118, v118
	v_exp_f32_e32 v119, v119
	s_waitcnt lgkmcnt(7)
	v_mfma_f32_32x32x16_bf16 v[86:101], v[188:191], v[154:157], v[86:101]
	ds_read_b128 v[188:191], v212 offset:49280
	v_add_f32_e32 v179, 0, v170
	v_add_f32_e32 v179, v171, v179
	v_add_f32_e32 v179, v172, v179
	v_add_f32_e32 v179, v173, v179
	v_add_f32_e32 v179, v174, v179
	s_waitcnt lgkmcnt(7)
	v_mfma_f32_32x32x16_bf16 v[70:85], v[228:231], v[154:157], v[70:85]
	ds_read_b128 v[228:231], v212 offset:57472
	v_add_f32_e32 v179, v176, v179
	v_add_f32_e32 v179, v175, v179
	v_add_f32_e32 v179, v177, v179
	v_add_f32_e32 v179, v162, v179
	v_add_f32_e32 v179, v163, v179
	s_waitcnt lgkmcnt(7)
	v_mfma_f32_32x32x16_bf16 v[86:101], v[232:235], v[150:153], v[86:101]
	ds_read_b128 v[232:235], v213 offset:49280
	v_add_f32_e32 v110, v164, v179
	v_add_f32_e32 v110, v166, v110
	v_add_f32_e32 v110, v165, v110
	v_add_f32_e32 v110, v167, v110
	s_waitcnt lgkmcnt(7)
	v_mfma_f32_32x32x16_bf16 v[70:85], v[236:239], v[150:153], v[70:85]
	ds_read_b128 v[236:239], v213 offset:57472
	v_add_f32_e32 v110, v168, v110
	v_add_f32_e32 v110, v169, v110
	v_add_f32_e32 v110, v126, v110
	v_add_f32_e32 v102, v127, v110
	s_waitcnt lgkmcnt(7)
	v_mfma_f32_32x32x16_bf16 v[86:101], v[240:243], v[134:137], v[86:101]
	ds_read_b128 v[240:243], v214 offset:49280
	v_add_f32_e32 v102, v124, v102
	v_add_f32_e32 v102, v125, v102
	v_add_f32_e32 v102, v120, v102
	v_add_f32_e32 v102, v121, v102
	s_waitcnt lgkmcnt(7)
	v_mfma_f32_32x32x16_bf16 v[70:85], v[244:247], v[134:137], v[70:85]
	ds_read_b128 v[244:247], v214 offset:57472
	v_add_f32_e32 v102, v116, v102
	v_add_f32_e32 v102, v117, v102
	v_add_f32_e32 v102, v114, v102
	v_add_f32_e32 v102, v115, v102
	s_waitcnt lgkmcnt(7)
	v_mfma_f32_32x32x16_bf16 v[86:101], v[180:183], v[138:141], v[86:101]
	v_add_f32_e32 v102, v128, v102
	v_add_f32_e32 v102, v129, v102
	v_add_f32_e32 v102, v122, v102
	v_add_f32_e32 v102, v123, v102
	s_waitcnt lgkmcnt(6)
	v_mfma_f32_32x32x16_bf16 v[70:85], v[184:187], v[138:141], v[70:85]
	v_add_f32_e32 v102, v118, v102
	v_add_f32_e32 v223, v119, v102
	v_mov_b32_e32 v224, v223
	s_nop 1
	v_permlane32_swap_b32_e32 v223, v224
	s_waitcnt lgkmcnt(5)
	v_mfma_f32_32x32x16_bf16 v[86:101], v[188:191], v[142:145], v[86:101]
	v_cvt_pk_bf16_f32 v102, v170, v171
	v_cvt_pk_bf16_f32 v103, v172, v173
	v_cvt_pk_bf16_f32 v104, v174, v176
	v_cvt_pk_bf16_f32 v105, v175, v177
	s_waitcnt lgkmcnt(4)
	v_mfma_f32_32x32x16_bf16 v[70:85], v[228:231], v[142:145], v[70:85]
	v_cvt_pk_bf16_f32 v66, v162, v163
	v_cvt_pk_bf16_f32 v67, v164, v166
	v_cvt_pk_bf16_f32 v68, v165, v167
	v_cvt_pk_bf16_f32 v69, v168, v169
	s_waitcnt lgkmcnt(3)
	v_mfma_f32_32x32x16_bf16 v[86:101], v[232:235], v[146:149], v[86:101]
	v_cvt_pk_bf16_f32 v106, v126, v127
	v_cvt_pk_bf16_f32 v107, v124, v125
	v_cvt_pk_bf16_f32 v108, v120, v121
	v_cvt_pk_bf16_f32 v109, v116, v117
	s_waitcnt lgkmcnt(2)
	v_mfma_f32_32x32x16_bf16 v[70:85], v[236:239], v[146:149], v[70:85]
	v_cvt_pk_bf16_f32 v110, v114, v115
	v_cvt_pk_bf16_f32 v111, v128, v129
	v_cvt_pk_bf16_f32 v112, v122, v123
	v_cvt_pk_bf16_f32 v113, v118, v119
	s_waitcnt lgkmcnt(1)
	v_mfma_f32_32x32x16_bf16 v[86:101], v[240:243], v[130:133], v[86:101]
	s_nop 1
	v_permlane32_swap_b32_e32 v102, v104
	v_permlane32_swap_b32_e32 v103, v105
	v_permlane32_swap_b32_e32 v66, v68
	v_permlane32_swap_b32_e32 v67, v69
	s_waitcnt lgkmcnt(0)
	v_mfma_f32_32x32x16_bf16 v[70:85], v[244:247], v[130:133], v[70:85]
	v_permlane32_swap_b32_e32 v106, v108
	v_permlane32_swap_b32_e32 v107, v109
	v_permlane32_swap_b32_e32 v110, v112
	v_permlane32_swap_b32_e32 v111, v113
	v_add_u32_e32 v114, 0x2000, v255
	global_load_dwordx4 v[162:165], v255, s[42:43]
	global_load_dwordx4 v[166:169], v114, s[42:43]
	s_cmp_le_i32 s5, s13
	s_cselect_b64 s[52:53], -1, 0
	s_cmp_gt_i32 s4, s15
	s_cselect_b64 s[4:5], -1, 0
	s_and_b64 s[4:5], s[52:53], s[4:5]
	s_and_b64 vcc, exec, s[4:5]
	ds_read_b64_tr_b16 v[114:115], v202 offset:0x0
	ds_read_b64_tr_b16 v[116:117], v202 offset:0x800
	ds_read_b64_tr_b16 v[118:119], v202 offset:0x1000
	ds_read_b64_tr_b16 v[120:121], v202 offset:0x1800
	ds_read_b64_tr_b16 v[122:123], v202 offset:0x2000
	ds_read_b64_tr_b16 v[124:125], v202 offset:0x2800
	ds_read_b64_tr_b16 v[126:127], v202 offset:0x3000
	ds_read_b64_tr_b16 v[128:129], v202 offset:0x3800
	ds_read_b64_tr_b16 v[182:183], v202 offset:0x200
	ds_read_b64_tr_b16 v[184:185], v202 offset:0xa00
	ds_read_b64_tr_b16 v[186:187], v202 offset:0x1200
	ds_read_b64_tr_b16 v[188:189], v202 offset:0x1a00
	ds_read_b64_tr_b16 v[190:191], v202 offset:0x2200
	ds_read_b64_tr_b16 v[192:193], v202 offset:0x2a00
	s_cbranch_vccnz .Lh1_nomask
; __device__ __forceinline__ void mask_tile(f32x16& p0, f32x16& p1, int dq, unsigned W) {
;     const float NEG = -__builtin_inff();
; #pragma unroll
;     for (int r = 0; r < 16; ++r) {
;         const int c = (r & 3) + 8 * (r >> 2);
;         if ((unsigned)(dq - c) >= W) p0[r] = NEG;
;         if ((unsigned)(dq - c - 32) >= W) p1[r] = NEG;
;     }
; }
	v_add_u32_e32 v226, s80, v222
	v_subrev_u32_e32 v240, 64, v226
	v_cmp_gt_u32_e32 vcc, s85, v240
	v_add_u32_e32 v240, 0xffffffa0, v226
	s_nop 0
	v_cndmask_b32_e32 v86, v215, v86, vcc
	v_cmp_gt_u32_e32 vcc, s85, v240
	v_add_u32_e32 v240, 0xffffffbf, v226
	s_nop 0
	v_cndmask_b32_e32 v70, v215, v70, vcc
	v_cmp_gt_u32_e32 vcc, s85, v240
	v_add_u32_e32 v240, 0xffffff9f, v226
	s_nop 0
	v_cndmask_b32_e32 v87, v215, v87, vcc
	v_cmp_gt_u32_e32 vcc, s85, v240
	v_add_u32_e32 v240, 0xffffffbe, v226
	s_nop 0
	v_cndmask_b32_e32 v71, v215, v71, vcc
	v_cmp_gt_u32_e32 vcc, s85, v240
	v_add_u32_e32 v240, 0xffffff9e, v226
	s_nop 0
	v_cndmask_b32_e32 v88, v215, v88, vcc
	v_cmp_gt_u32_e32 vcc, s85, v240
	v_add_u32_e32 v240, 0xffffffbd, v226
	s_nop 0
	v_cndmask_b32_e32 v72, v215, v72, vcc
	v_cmp_gt_u32_e32 vcc, s85, v240
	v_add_u32_e32 v240, 0xffffff9d, v226
	s_nop 0
	v_cndmask_b32_e32 v89, v215, v89, vcc
	v_cmp_gt_u32_e32 vcc, s85, v240
	v_add_u32_e32 v240, 0xffffffb8, v226
	s_nop 0
	v_cndmask_b32_e32 v73, v215, v73, vcc
	v_cmp_gt_u32_e32 vcc, s85, v240
	v_add_u32_e32 v240, 0xffffff98, v226
	s_nop 0
	v_cndmask_b32_e32 v90, v215, v90, vcc
	v_cmp_gt_u32_e32 vcc, s85, v240
	v_add_u32_e32 v240, 0xffffffb7, v226
	s_nop 0
	v_cndmask_b32_e32 v74, v215, v74, vcc
	v_cmp_gt_u32_e32 vcc, s85, v240
	v_add_u32_e32 v240, 0xffffff97, v226
	s_nop 0
	v_cndmask_b32_e32 v91, v215, v91, vcc
	v_cmp_gt_u32_e32 vcc, s85, v240
	v_add_u32_e32 v240, 0xffffffb6, v226
	s_nop 0
	v_cndmask_b32_e32 v75, v215, v75, vcc
	v_cmp_gt_u32_e32 vcc, s85, v240
	v_add_u32_e32 v240, 0xffffff96, v226
	s_nop 0
	v_cndmask_b32_e32 v92, v215, v92, vcc
	v_cmp_gt_u32_e32 vcc, s85, v240
	v_add_u32_e32 v240, 0xffffffb5, v226
	s_nop 0
	v_cndmask_b32_e32 v76, v215, v76, vcc
	v_cmp_gt_u32_e32 vcc, s85, v240
	v_add_u32_e32 v240, 0xffffff95, v226
	s_nop 0
	v_cndmask_b32_e32 v93, v215, v93, vcc
	v_cmp_gt_u32_e32 vcc, s85, v240
	v_add_u32_e32 v240, 0xffffffb0, v226
	s_nop 0
	v_cndmask_b32_e32 v77, v215, v77, vcc
	v_cmp_gt_u32_e32 vcc, s85, v240
	v_add_u32_e32 v240, 0xffffff90, v226
	s_nop 0
	v_cndmask_b32_e32 v94, v215, v94, vcc
	v_cmp_gt_u32_e32 vcc, s85, v240
	v_add_u32_e32 v240, 0xffffffaf, v226
	s_nop 0
	v_cndmask_b32_e32 v78, v215, v78, vcc
	v_cmp_gt_u32_e32 vcc, s85, v240
	v_add_u32_e32 v240, 0xffffff8f, v226
	s_nop 0
	v_cndmask_b32_e32 v95, v215, v95, vcc
	v_cmp_gt_u32_e32 vcc, s85, v240
	v_add_u32_e32 v240, 0xffffffae, v226
	s_nop 0
	v_cndmask_b32_e32 v79, v215, v79, vcc
	v_cmp_gt_u32_e32 vcc, s85, v240
	v_add_u32_e32 v240, 0xffffff8e, v226
	s_nop 0
	v_cndmask_b32_e32 v96, v215, v96, vcc
	v_cmp_gt_u32_e32 vcc, s85, v240
	v_add_u32_e32 v240, 0xffffffad, v226
	s_nop 0
	v_cndmask_b32_e32 v80, v215, v80, vcc
	v_cmp_gt_u32_e32 vcc, s85, v240
	v_add_u32_e32 v240, 0xffffff8d, v226
	s_nop 0
	v_cndmask_b32_e32 v97, v215, v97, vcc
	v_cmp_gt_u32_e32 vcc, s85, v240
	v_add_u32_e32 v240, 0xffffffa8, v226
	s_nop 0
	v_cndmask_b32_e32 v81, v215, v81, vcc
	v_cmp_gt_u32_e32 vcc, s85, v240
	v_add_u32_e32 v240, 0xffffff88, v226
	s_nop 0
	v_cndmask_b32_e32 v98, v215, v98, vcc
	v_cmp_gt_u32_e32 vcc, s85, v240
	v_add_u32_e32 v240, 0xffffffa7, v226
	s_nop 0
	v_cndmask_b32_e32 v82, v215, v82, vcc
	v_cmp_gt_u32_e32 vcc, s85, v240
	v_add_u32_e32 v240, 0xffffff87, v226
	s_nop 0
	v_cndmask_b32_e32 v99, v215, v99, vcc
	v_cmp_gt_u32_e32 vcc, s85, v240
	v_add_u32_e32 v240, 0xffffffa6, v226
	s_nop 0
	v_cndmask_b32_e32 v83, v215, v83, vcc
	v_cmp_gt_u32_e32 vcc, s85, v240
	v_add_u32_e32 v240, 0xffffff86, v226
	s_nop 0
	v_cndmask_b32_e32 v100, v215, v100, vcc
	v_cmp_gt_u32_e32 vcc, s85, v240
	v_add_u32_e32 v240, 0xffffffa5, v226
	s_nop 0
	v_cndmask_b32_e32 v84, v215, v84, vcc
	v_cmp_gt_u32_e32 vcc, s85, v240
	v_add_u32_e32 v240, 0xffffff85, v226
	s_nop 0
	v_cndmask_b32_e32 v101, v215, v101, vcc
	v_cmp_gt_u32_e32 vcc, s85, v240
	s_nop 1
	v_cndmask_b32_e32 v85, v215, v85, vcc

; __device__ __forceinline__ void finishSM(f32x16& p0, f32x16& p1, float alpha, float& l_reg, bf16x8& pa0, bf16x8& pa1, bf16x8& pa2, bf16x8& pa3) {
;     for (int r = 0; r < 16; ++r) p1[r] = __builtin_amdgcn_exp2f(p1[r]);
;     float ps = 0; for (int r = 0; r < 16; ++r) ps += p0[r]; for (int r = 0; r < 16; ++r) ps += p1[r];
;     { auto rr = __builtin_amdgcn_permlane32_swap(__float_as_uint(ps), __float_as_uint(ps), false, false);
;       ps = __uint_as_float(rr[0]) + __uint_as_float(rr[1]); }
;     l_reg = l_reg * alpha + ps;
;     ...
;     PK4(p0, 0, pa0); PK4(p0, 8, pa1); PK4(p1, 0, pa2); PK4(p1, 8, pa3);
;     ...
; }
; template <int KB, bool SK>
; __device__ __forceinline__ void qkt(f32x16& p0, f32x16& p1, const char* K_lds, int r32, int hi, const bf16x8* qr, bool act) {
;     if (SK && !act) { const float NEG = -__builtin_inff();
; #pragma unroll
;         for (int r = 0; r < 16; ++r) { p0[r] = NEG; p1[r] = NEG; } return; }
;     p0 = f32x16{}; p1 = f32x16{};
;     const char* kb[4];
; #pragma unroll
;     for (int dd = 0; dd < 4; ++dd) kb[dd] = K_lds + KB * SHM_K + KSWZ(r32, (dd * 16 + hi * 8) * 2);
; #pragma unroll
;     for (int d0 = 0; d0 < 8; ++d0) { const char* a = kb[d0 & 3] + (d0 >> 2) * 128;
;         bf16x8 b0 = *reinterpret_cast<const bf16x8*>(a);
;         bf16x8 b1 = *reinterpret_cast<const bf16x8*>(a + 32 * 256);
;         const bf16x8 qf = qr[d0];
;         p0 = __builtin_amdgcn_mfma_f32_32x32x16_bf16(b0, qf, p0, 0, 0, 0);
;         p1 = __builtin_amdgcn_mfma_f32_32x32x16_bf16(b1, qf, p1, 0, 0, 0); }
; }
.Lh1_noresc:
	v_exp_f32_e32 v66, v228
	v_exp_f32_e32 v67, v229
	v_exp_f32_e32 v68, v230
	v_exp_f32_e32 v69, v231
	v_exp_f32_e32 v70, v232
	v_exp_f32_e32 v71, v233
	v_exp_f32_e32 v72, v234
	v_exp_f32_e32 v73, v235
	v_exp_f32_e32 v74, v236
	v_exp_f32_e32 v75, v237
	v_exp_f32_e32 v76, v238
	v_exp_f32_e32 v77, v239
	v_exp_f32_e32 v78, v98
	v_exp_f32_e32 v79, v99
	v_exp_f32_e32 v80, v100
	v_exp_f32_e32 v81, v101
	s_waitcnt lgkmcnt(0)
	s_barrier
	s_add_i32 s52, s25, 1
	s_cmp_gt_u32 s52, s24
	s_cbranch_scc1 .Lh2_skipk
	v_readfirstlane_b32 s52, v1
	v_add_u32_e32 v248, 0x4000, v251
	v_add_u32_e32 v249, 0x6000, v251
	s_nop 0
	s_lshl_b32 s52, s52, 4
	s_add_i32 m0, s52, 0xc000
	s_nop 0
	global_load_lds_dwordx4 v248, s[22:23]
	s_add_i32 m0, s52, 0xe000
	s_nop 0
	global_load_lds_dwordx4 v249, s[22:23]
.Lh2_skipk:
	ds_read_b128 v[162:165], v211 offset:32768
	ds_read_b128 v[166:169], v211 offset:40960
	ds_read_b128 v[170:173], v212 offset:32768
	ds_read_b128 v[174:177], v212 offset:40960
	ds_read_b128 v[230:233], v213 offset:32768
	ds_read_b128 v[234:237], v213 offset:40960
	ds_read_b128 v[238:241], v214 offset:32768
	ds_read_b128 v[242:245], v214 offset:40960
	v_exp_f32_e32 v82, v86
	v_exp_f32_e32 v83, v95
	v_exp_f32_e32 v84, v96
	v_exp_f32_e32 v85, v97
	v_exp_f32_e32 v86, v179
	v_exp_f32_e32 v87, v87
	s_waitcnt lgkmcnt(7)
	v_mfma_f32_32x32x16_bf16 v[114:129], v[162:165], v[158:161], 0
	ds_read_b128 v[162:165], v211 offset:32896
	v_exp_f32_e32 v88, v88
	v_exp_f32_e32 v89, v89
	v_exp_f32_e32 v90, v90
	v_exp_f32_e32 v91, v91
	v_exp_f32_e32 v92, v92
	s_waitcnt lgkmcnt(7)
	v_mfma_f32_32x32x16_bf16 v[98:113], v[166:169], v[158:161], 0
	ds_read_b128 v[166:169], v211 offset:41088
	v_exp_f32_e32 v93, v93
	v_exp_f32_e32 v94, v94
	v_exp_f32_e32 v95, v180
	v_exp_f32_e32 v96, v181
	v_exp_f32_e32 v97, v178
	s_waitcnt lgkmcnt(7)
	v_mfma_f32_32x32x16_bf16 v[114:129], v[170:173], v[154:157], v[114:129]
	ds_read_b128 v[170:173], v212 offset:32896
	v_add_f32_e32 v178, 0, v66
	v_add_f32_e32 v178, v67, v178
	v_add_f32_e32 v178, v68, v178
	v_add_f32_e32 v178, v69, v178
	v_add_f32_e32 v178, v70, v178
	s_waitcnt lgkmcnt(7)
	v_mfma_f32_32x32x16_bf16 v[98:113], v[174:177], v[154:157], v[98:113]
	ds_read_b128 v[174:177], v212 offset:41088
	v_add_f32_e32 v178, v71, v178
	v_add_f32_e32 v178, v72, v178
	v_add_f32_e32 v178, v73, v178
	v_add_f32_e32 v178, v74, v178
	v_add_f32_e32 v178, v75, v178
	s_waitcnt lgkmcnt(7)
	v_mfma_f32_32x32x16_bf16 v[114:129], v[230:233], v[150:153], v[114:129]
	ds_read_b128 v[230:233], v213 offset:32896
	v_add_f32_e32 v178, v76, v178
	v_add_f32_e32 v178, v77, v178
	v_add_f32_e32 v178, v78, v178
	v_add_f32_e32 v178, v79, v178
	s_waitcnt lgkmcnt(7)
	v_mfma_f32_32x32x16_bf16 v[98:113], v[234:237], v[150:153], v[98:113]
	ds_read_b128 v[234:237], v213 offset:41088
	v_add_f32_e32 v178, v80, v178
	v_add_f32_e32 v178, v81, v178
	v_add_f32_e32 v178, v82, v178
	v_add_f32_e32 v178, v83, v178
	s_waitcnt lgkmcnt(7)
	v_mfma_f32_32x32x16_bf16 v[114:129], v[238:241], v[134:137], v[114:129]
	ds_read_b128 v[238:241], v214 offset:32896
	v_add_f32_e32 v178, v84, v178
	v_add_f32_e32 v178, v85, v178
	v_add_f32_e32 v178, v86, v178
	v_add_f32_e32 v178, v87, v178
	s_waitcnt lgkmcnt(7)
	v_mfma_f32_32x32x16_bf16 v[98:113], v[242:245], v[134:137], v[98:113]
	ds_read_b128 v[242:245], v214 offset:41088
	v_add_f32_e32 v178, v88, v178
	v_add_f32_e32 v178, v89, v178
	v_add_f32_e32 v178, v90, v178
	v_add_f32_e32 v178, v91, v178
	s_waitcnt lgkmcnt(7)
	v_mfma_f32_32x32x16_bf16 v[114:129], v[162:165], v[138:141], v[114:129]
	v_add_f32_e32 v178, v92, v178
	v_add_f32_e32 v178, v93, v178
	v_add_f32_e32 v178, v94, v178
	v_add_f32_e32 v178, v95, v178
	s_waitcnt lgkmcnt(6)
	v_mfma_f32_32x32x16_bf16 v[98:113], v[166:169], v[138:141], v[98:113]
	v_add_f32_e32 v178, v96, v178
	v_add_f32_e32 v228, v97, v178
	v_mov_b32_e32 v229, v228
	s_nop 1
	v_permlane32_swap_b32_e32 v228, v229
	s_waitcnt lgkmcnt(5)
	v_mfma_f32_32x32x16_bf16 v[114:129], v[170:173], v[142:145], v[114:129]
	v_cvt_pk_bf16_f32 v178, v66, v67
	v_cvt_pk_bf16_f32 v179, v68, v69
	v_cvt_pk_bf16_f32 v180, v70, v71
	v_cvt_pk_bf16_f32 v181, v72, v73
	s_waitcnt lgkmcnt(4)
	v_mfma_f32_32x32x16_bf16 v[98:113], v[174:177], v[142:145], v[98:113]
	v_cvt_pk_bf16_f32 v182, v74, v75
	v_cvt_pk_bf16_f32 v183, v76, v77
	v_cvt_pk_bf16_f32 v184, v78, v79
	v_cvt_pk_bf16_f32 v185, v80, v81
	s_waitcnt lgkmcnt(3)
	v_mfma_f32_32x32x16_bf16 v[114:129], v[230:233], v[146:149], v[114:129]
	v_cvt_pk_bf16_f32 v186, v82, v83
	v_cvt_pk_bf16_f32 v187, v84, v85
	v_cvt_pk_bf16_f32 v188, v86, v87
	v_cvt_pk_bf16_f32 v189, v88, v89
	s_waitcnt lgkmcnt(2)
	v_mfma_f32_32x32x16_bf16 v[98:113], v[234:237], v[146:149], v[98:113]
	v_cvt_pk_bf16_f32 v190, v90, v91
	v_cvt_pk_bf16_f32 v191, v92, v93
	v_cvt_pk_bf16_f32 v192, v94, v95
	v_cvt_pk_bf16_f32 v193, v96, v97
	s_waitcnt lgkmcnt(1)
	v_mfma_f32_32x32x16_bf16 v[114:129], v[238:241], v[130:133], v[114:129]
	s_nop 1
	v_permlane32_swap_b32_e32 v178, v180
	v_permlane32_swap_b32_e32 v179, v181
	v_permlane32_swap_b32_e32 v182, v184
	v_permlane32_swap_b32_e32 v183, v185
	s_waitcnt lgkmcnt(0)
	v_mfma_f32_32x32x16_bf16 v[98:113], v[242:245], v[130:133], v[98:113]
	v_permlane32_swap_b32_e32 v186, v188
	v_permlane32_swap_b32_e32 v187, v189
	v_permlane32_swap_b32_e32 v190, v192
	v_permlane32_swap_b32_e32 v191, v193
	s_add_i32 s4, s25, 1
	s_cmp_le_u32 s4, s24
	s_cselect_b64 s[76:77], -1, 0
	s_cmp_gt_u32 s4, s24
	s_cbranch_scc1 .LBB0_1137
	v_add_u32_e32 v84, 0x4000, v255
	v_add_u32_e32 v85, 0x6000, v255
	global_load_dwordx4 v[162:165], v84, s[42:43]
	global_load_dwordx4 v[166:169], v85, s[42:43]
